# last GEMM tail (phase 12, E5B) converted to the coalesced-load + per-wave LDS staged K loop; all 9 tails now converted
# speedup vs baseline: 1.0001x; 1.0001x over previous
; DI f32x16 mfma32(bf16x8 a, bf16x8 b, f32x16 c) { return __builtin_amdgcn_mfma_f32_32x32x16_bf16(a, b, c, 0, 0, 0); }
; DI f32x16 zero16() { f32x16 z; for (int i = 0; i < 16; ++i) z[i] = 0.f; return z; }
; DI int opaque_tid() { int t = threadIdx.x; asm volatile("" : "+v"(t)); return t; }
; template <int EPI, int K, int LNI>
; DI void gemm_tail_unit(const Params& p, const bf16_t* __restrict__ A, const bf16_t* __restrict__ Bt, const int un, float* s_aux) {
;     const int tid = opaque_tid(), lane = tid & 63, w = tid >> 6, r = lane & 31, h = lane >> 5;
;     constexpr int ROW0 = 32768, KS = K / 8;
;     const int col0 = un * 64;
;     if (EPI == EPI_E5B) {
;         if (tid < 64) {
;             const int hd = col0 >> 9;
;             const float* pp = (const float*)((unsigned char*)p.out + OFFO_PART) + (size_t)(ROW0 + tid) * 256 + hd * 64;
;             float sacc = 0.f;
; #pragma unroll
;             for (int i = 0; i < 16; ++i) { const f32x4 v = *(const f32x4*)(pp + i * 4); sacc += (v[0] + v[1]) + (v[2] + v[3]); }
;             s_aux[tid] = __frsqrt_rn(sacc * (1.0f / 512.0f) + 1e-6f);
;         }
;     }
;     f32x16 acc[2][2];
;     acc[0][0] = zero16(); acc[0][1] = zero16(); acc[1][0] = zero16(); acc[1][1] = zero16();
;     const bf16_t* ap = A + (size_t)(ROW0 + r) * K + w * KS + h * 8;
;     const bf16_t* bp = Bt + (size_t)(col0 + r) * K + w * KS + h * 8;
; #pragma unroll 8
;     for (int s = 0; s < KS / 16; ++s) {
;         const bf16x8 a0 = *(const bf16x8*)(ap + s * 16), a1 = *(const bf16x8*)(ap + (size_t)32 * K + s * 16);
;         const bf16x8 b0 = *(const bf16x8*)(bp + s * 16), b1 = *(const bf16x8*)(bp + (size_t)32 * K + s * 16);
;         acc[0][0] = mfma32(a0, b0, acc[0][0]); acc[0][1] = mfma32(a0, b1, acc[0][1]);
;         acc[1][0] = mfma32(a1, b0, acc[1][0]); acc[1][1] = mfma32(a1, b1, acc[1][1]);
;     }
.LBB0_1644:
	s_or_b64 exec, exec, s[10:11]
	v_ashrrev_i32_e32 v117, 6, v66
	v_and_b32_e32 v67, 31, v66
	v_lshlrev_b32_e32 v2, 7, v117
	v_lshlrev_b32_e32 v64, 11, v67
	v_ashrrev_i32_e32 v3, 31, v2
	v_bfe_u32 v116, v66, 5, 1
	v_lshl_add_u64 v[0:1], s[40:41], 0, v[64:65]
	v_lshlrev_b64 v[4:5], 1, v[2:3]
	v_lshl_add_u64 v[0:1], v[0:1], 0, v[4:5]
	v_lshlrev_b32_e32 v6, 4, v116
	v_mov_b32_e32 v7, v65
	v_add_u32_e32 v106, s3, v67
	v_lshl_add_u64 v[12:13], v[0:1], 0, v[6:7]
	v_ashrrev_i32_e32 v107, 31, v106
	v_lshlrev_b64 v[8:9], 11, v[106:107]
	v_add_co_u32_e32 v0, vcc, s15, v12
	v_lshl_add_u64 v[8:9], s[22:23], 0, v[8:9]
	s_nop 0
	v_addc_co_u32_e32 v1, vcc, 0, v13, vcc
	s_nop 0
	v_readfirstlane_b32 s88, v0
	v_readfirstlane_b32 s89, v1
	v_lshl_add_u64 v[4:5], v[8:9], 0, v[4:5]
	v_lshl_add_u64 v[108:109], v[4:5], 0, v[6:7]
	v_add_co_u32_e32 v112, vcc, s27, v108
	v_lshl_add_u64 v[110:111], v[12:13], 0, s[8:9]
	s_nop 0
	v_addc_co_u32_e32 v113, vcc, 0, v109, vcc
	s_nop 0
	v_readfirstlane_b32 s90, v108
	v_readfirstlane_b32 s91, v109
	v_add_co_u32_e32 v114, vcc, s26, v12
	v_lshlrev_b32_e32 v64, 3, v116
	s_nop 0
	v_addc_co_u32_e32 v115, vcc, 0, v13, vcc
	s_add_i32 s45, s45, s58
	s_add_i32 s44, s44, s34
	v_and_b32_e32 v90, 63, v66
	v_lshl_add_u32 v90, v90, 2, 0
	v_lshl_add_u32 v91, v117, 14, v90
	s_nop 11
	s_nop 6
	s_nop 5
	v_and_b32_e32 v244, 63, v210
	v_lshrrev_b32_e32 v245, 3, v244
	v_and_b32_e32 v249, 7, v244
	v_lshlrev_b32_e32 v247, 11, v245
	v_lshl_add_u32 v247, v249, 4, v247
	v_lshrrev_b32_e32 v248, 6, v210
	v_lshlrev_b32_e32 v248, 14, v248
	v_mul_u32_u24_e32 v245, 0x90, v245
	v_lshl_add_u32 v245, v249, 4, v245
	v_add_u32_e32 v245, v245, v248
	v_and_b32_e32 v246, 31, v210
	v_mul_u32_u24_e32 v246, 0x90, v246
	v_bfe_u32 v249, v210, 5, 1
	v_lshl_add_u32 v246, v249, 4, v246
	v_add_u32_e32 v246, v246, v248
	global_load_dwordx4 v[72:75], v247, s[88:89]
	s_add_u32 s92, s88, 0x4000
	s_addc_u32 s93, s89, 0
	s_nop 0
	global_load_dwordx4 v[76:79], v247, s[92:93]
	s_add_u32 s94, s88, 0x8000
	s_addc_u32 s95, s89, 0
	s_nop 0
	global_load_dwordx4 v[80:83], v247, s[94:95]
	s_add_u32 s92, s88, 0xc000
	s_addc_u32 s93, s89, 0
	s_nop 0
	global_load_dwordx4 v[84:87], v247, s[92:93]
	s_add_u32 s94, s88, 0x10000
	s_addc_u32 s95, s89, 0
	s_nop 0
	global_load_dwordx4 v[92:95], v247, s[94:95]
	s_add_u32 s92, s88, 0x14000
	s_addc_u32 s93, s89, 0
	s_nop 0
	global_load_dwordx4 v[96:99], v247, s[92:93]
	s_add_u32 s94, s88, 0x18000
	s_addc_u32 s95, s89, 0
	s_nop 0
	global_load_dwordx4 v[100:103], v247, s[94:95]
	s_add_u32 s92, s88, 0x1c000
	s_addc_u32 s93, s89, 0
	s_nop 0
	global_load_dwordx4 v[120:123], v247, s[92:93]
	global_load_dwordx4 v[124:127], v247, s[90:91]
	s_add_u32 s94, s90, 0x4000
	s_addc_u32 s95, s91, 0
	s_nop 0
	global_load_dwordx4 v[128:131], v247, s[94:95]
	s_add_u32 s92, s90, 0x8000
	s_addc_u32 s93, s91, 0
	s_nop 0
	global_load_dwordx4 v[132:135], v247, s[92:93]
	s_add_u32 s94, s90, 0xc000
	s_addc_u32 s95, s91, 0
	s_nop 0
	global_load_dwordx4 v[136:139], v247, s[94:95]
	s_add_u32 s92, s90, 0x10000
	s_addc_u32 s93, s91, 0
	s_nop 0
	global_load_dwordx4 v[140:143], v247, s[92:93]
	s_add_u32 s94, s90, 0x14000
	s_addc_u32 s95, s91, 0
	s_nop 0
	global_load_dwordx4 v[144:147], v247, s[94:95]
	s_add_u32 s92, s90, 0x18000
	s_addc_u32 s93, s91, 0
	s_nop 0
	global_load_dwordx4 v[148:151], v247, s[92:93]
	s_add_u32 s94, s90, 0x1c000
	s_addc_u32 s95, s91, 0
	s_nop 0
	global_load_dwordx4 v[152:155], v247, s[94:95]
	global_load_dwordx4 v[156:159], v247, s[88:89] offset:128
	s_add_u32 s92, s88, 0x4000
	s_addc_u32 s93, s89, 0
	s_nop 0
	global_load_dwordx4 v[160:163], v247, s[92:93] offset:128
	s_add_u32 s94, s88, 0x8000
	s_addc_u32 s95, s89, 0
	s_nop 0
	global_load_dwordx4 v[164:167], v247, s[94:95] offset:128
	s_add_u32 s92, s88, 0xc000
	s_addc_u32 s93, s89, 0
	s_nop 0
	global_load_dwordx4 v[168:171], v247, s[92:93] offset:128
	s_add_u32 s94, s88, 0x10000
	s_addc_u32 s95, s89, 0
	s_nop 0
	global_load_dwordx4 v[172:175], v247, s[94:95] offset:128
	s_add_u32 s92, s88, 0x14000
	s_addc_u32 s93, s89, 0
	s_nop 0
	global_load_dwordx4 v[176:179], v247, s[92:93] offset:128
	s_add_u32 s94, s88, 0x18000
	s_addc_u32 s95, s89, 0
	s_nop 0
	global_load_dwordx4 v[180:183], v247, s[94:95] offset:128
	s_add_u32 s92, s88, 0x1c000
	s_addc_u32 s93, s89, 0
	s_nop 0
	global_load_dwordx4 v[184:187], v247, s[92:93] offset:128
	global_load_dwordx4 v[188:191], v247, s[90:91] offset:128
	s_add_u32 s94, s90, 0x4000
	s_addc_u32 s95, s91, 0
	s_nop 0
	global_load_dwordx4 v[192:195], v247, s[94:95] offset:128
	s_add_u32 s92, s90, 0x8000
	s_addc_u32 s93, s91, 0
	s_nop 0
	global_load_dwordx4 v[196:199], v247, s[92:93] offset:128
	s_add_u32 s94, s90, 0xc000
	s_addc_u32 s95, s91, 0
	s_nop 0
	global_load_dwordx4 v[200:203], v247, s[94:95] offset:128
	s_add_u32 s92, s90, 0x10000
	s_addc_u32 s93, s91, 0
	s_nop 0
	global_load_dwordx4 v[204:207], v247, s[92:93] offset:128
	s_add_u32 s94, s90, 0x14000
	s_addc_u32 s95, s91, 0
	s_nop 0
	global_load_dwordx4 v[212:215], v247, s[94:95] offset:128
	s_add_u32 s92, s90, 0x18000
	s_addc_u32 s93, s91, 0
	s_nop 0
	global_load_dwordx4 v[216:219], v247, s[92:93] offset:128
	s_add_u32 s94, s90, 0x1c000
	s_addc_u32 s95, s91, 0
	s_nop 0
	global_load_dwordx4 v[220:223], v247, s[94:95] offset:128
	s_waitcnt vmcnt(24) lgkmcnt(0)
	ds_write_b128 v245, v[72:75]
	ds_write_b128 v245, v[76:79] offset:1152
	ds_write_b128 v245, v[80:83] offset:2304
	ds_write_b128 v245, v[84:87] offset:3456
	ds_write_b128 v245, v[92:95] offset:4608
	ds_write_b128 v245, v[96:99] offset:5760
	ds_write_b128 v245, v[100:103] offset:6912
	ds_write_b128 v245, v[120:123] offset:8064
	s_waitcnt lgkmcnt(0)
; DI f32x16 mfma32(bf16x8 a, bf16x8 b, f32x16 c) { return __builtin_amdgcn_mfma_f32_32x32x16_bf16(a, b, c, 0, 0, 0); }
; template <int EPI, int K, int LNI>
; DI void gemm_tail_unit(const Params& p, const bf16_t* __restrict__ A, const bf16_t* __restrict__ Bt, const int un, float* s_aux) {
;     ...
; #pragma unroll 8
;     for (int s = 0; s < KS / 16; ++s) {
;         const bf16x8 a0 = *(const bf16x8*)(ap + s * 16), a1 = *(const bf16x8*)(ap + (size_t)32 * K + s * 16);
;         const bf16x8 b0 = *(const bf16x8*)(bp + s * 16), b1 = *(const bf16x8*)(bp + (size_t)32 * K + s * 16);
;         acc[0][0] = mfma32(a0, b0, acc[0][0]); acc[0][1] = mfma32(a0, b1, acc[0][1]);
;         acc[1][0] = mfma32(a1, b0, acc[1][0]); acc[1][1] = mfma32(a1, b1, acc[1][1]);
;     }
;     float* red = (float*)dsm;
; #pragma unroll
;     for (int i = 0; i < 2; ++i)
; #pragma unroll
;         for (int j = 0; j < 2; ++j)
; #pragma unroll
;             for (int reg = 0; reg < 16; ++reg) red[((w * 4 + i * 2 + j) * 16 + reg) * 64 + lane] = acc[i][j][reg];
;     __syncthreads();
	ds_read_b128 v[72:75], v246
	ds_read_b128 v[76:79], v246 offset:32
	ds_read_b128 v[80:83], v246 offset:64
	ds_read_b128 v[84:87], v246 offset:96
	ds_read_b128 v[92:95], v246 offset:4608
	ds_read_b128 v[96:99], v246 offset:4640
	ds_read_b128 v[100:103], v246 offset:4672
	ds_read_b128 v[120:123], v246 offset:4704
	s_waitcnt vmcnt(16) lgkmcnt(0)
	ds_write_b128 v245, v[124:127]
	ds_write_b128 v245, v[128:131] offset:1152
	ds_write_b128 v245, v[132:135] offset:2304
	ds_write_b128 v245, v[136:139] offset:3456
	ds_write_b128 v245, v[140:143] offset:4608
	ds_write_b128 v245, v[144:147] offset:5760
	ds_write_b128 v245, v[148:151] offset:6912
	ds_write_b128 v245, v[152:155] offset:8064
	s_waitcnt lgkmcnt(0)
	ds_read_b128 v[124:127], v246
	ds_read_b128 v[128:131], v246 offset:32
	ds_read_b128 v[132:135], v246 offset:64
	ds_read_b128 v[136:139], v246 offset:96
	ds_read_b128 v[140:143], v246 offset:4608
	ds_read_b128 v[144:147], v246 offset:4640
	ds_read_b128 v[148:151], v246 offset:4672
	ds_read_b128 v[152:155], v246 offset:4704
	s_waitcnt lgkmcnt(0)
	v_mfma_f32_32x32x16_bf16 v[48:63], v[72:75], v[124:127], 0
	v_mfma_f32_32x32x16_bf16 v[32:47], v[72:75], v[140:143], 0
	v_mfma_f32_32x32x16_bf16 v[16:31], v[92:95], v[124:127], 0
	v_mfma_f32_32x32x16_bf16 v[0:15], v[92:95], v[140:143], 0
	v_mfma_f32_32x32x16_bf16 v[48:63], v[76:79], v[128:131], v[48:63]
	v_mfma_f32_32x32x16_bf16 v[32:47], v[76:79], v[144:147], v[32:47]
	v_mfma_f32_32x32x16_bf16 v[16:31], v[96:99], v[128:131], v[16:31]
	v_mfma_f32_32x32x16_bf16 v[0:15], v[96:99], v[144:147], v[0:15]
	v_mfma_f32_32x32x16_bf16 v[48:63], v[80:83], v[132:135], v[48:63]
	v_mfma_f32_32x32x16_bf16 v[32:47], v[80:83], v[148:151], v[32:47]
	v_mfma_f32_32x32x16_bf16 v[16:31], v[100:103], v[132:135], v[16:31]
	v_mfma_f32_32x32x16_bf16 v[0:15], v[100:103], v[148:151], v[0:15]
	v_mfma_f32_32x32x16_bf16 v[48:63], v[84:87], v[136:139], v[48:63]
	v_mfma_f32_32x32x16_bf16 v[32:47], v[84:87], v[152:155], v[32:47]
	v_mfma_f32_32x32x16_bf16 v[16:31], v[120:123], v[136:139], v[16:31]
	v_mfma_f32_32x32x16_bf16 v[0:15], v[120:123], v[152:155], v[0:15]
	s_waitcnt vmcnt(8) lgkmcnt(0)
	ds_write_b128 v245, v[156:159]
	ds_write_b128 v245, v[160:163] offset:1152
	ds_write_b128 v245, v[164:167] offset:2304
	ds_write_b128 v245, v[168:171] offset:3456
	ds_write_b128 v245, v[172:175] offset:4608
	ds_write_b128 v245, v[176:179] offset:5760
	ds_write_b128 v245, v[180:183] offset:6912
	ds_write_b128 v245, v[184:187] offset:8064
	s_waitcnt lgkmcnt(0)
	ds_read_b128 v[156:159], v246
	ds_read_b128 v[160:163], v246 offset:32
	ds_read_b128 v[164:167], v246 offset:64
	ds_read_b128 v[168:171], v246 offset:96
	ds_read_b128 v[172:175], v246 offset:4608
	ds_read_b128 v[176:179], v246 offset:4640
	ds_read_b128 v[180:183], v246 offset:4672
	ds_read_b128 v[184:187], v246 offset:4704
	s_waitcnt vmcnt(0) lgkmcnt(0)
	ds_write_b128 v245, v[188:191]
	ds_write_b128 v245, v[192:195] offset:1152
	ds_write_b128 v245, v[196:199] offset:2304
	ds_write_b128 v245, v[200:203] offset:3456
	ds_write_b128 v245, v[204:207] offset:4608
	ds_write_b128 v245, v[212:215] offset:5760
	ds_write_b128 v245, v[216:219] offset:6912
	ds_write_b128 v245, v[220:223] offset:8064
	s_waitcnt lgkmcnt(0)
	ds_read_b128 v[188:191], v246
	ds_read_b128 v[192:195], v246 offset:32
	ds_read_b128 v[196:199], v246 offset:64
	ds_read_b128 v[200:203], v246 offset:96
	ds_read_b128 v[204:207], v246 offset:4608
	ds_read_b128 v[212:215], v246 offset:4640
	ds_read_b128 v[216:219], v246 offset:4672
	ds_read_b128 v[220:223], v246 offset:4704
	s_waitcnt lgkmcnt(0)
	v_mfma_f32_32x32x16_bf16 v[48:63], v[156:159], v[188:191], v[48:63]
	v_mfma_f32_32x32x16_bf16 v[32:47], v[156:159], v[204:207], v[32:47]
	v_mfma_f32_32x32x16_bf16 v[16:31], v[172:175], v[188:191], v[16:31]
	v_mfma_f32_32x32x16_bf16 v[0:15], v[172:175], v[204:207], v[0:15]
	v_mfma_f32_32x32x16_bf16 v[48:63], v[160:163], v[192:195], v[48:63]
	v_mfma_f32_32x32x16_bf16 v[32:47], v[160:163], v[212:215], v[32:47]
	v_mfma_f32_32x32x16_bf16 v[16:31], v[176:179], v[192:195], v[16:31]
	v_mfma_f32_32x32x16_bf16 v[0:15], v[176:179], v[212:215], v[0:15]
	v_mfma_f32_32x32x16_bf16 v[48:63], v[164:167], v[196:199], v[48:63]
	v_mfma_f32_32x32x16_bf16 v[32:47], v[164:167], v[216:219], v[32:47]
	v_mfma_f32_32x32x16_bf16 v[16:31], v[180:183], v[196:199], v[16:31]
	v_mfma_f32_32x32x16_bf16 v[0:15], v[180:183], v[216:219], v[0:15]
	v_mfma_f32_32x32x16_bf16 v[48:63], v[168:171], v[200:203], v[48:63]
	v_mfma_f32_32x32x16_bf16 v[32:47], v[168:171], v[220:223], v[32:47]
	v_mfma_f32_32x32x16_bf16 v[16:31], v[184:187], v[200:203], v[16:31]
	v_mfma_f32_32x32x16_bf16 v[0:15], v[184:187], v[220:223], v[0:15]
	s_nop 7
	s_nop 3
	ds_write2st64_b32 v91, v48, v49 offset1:1
	ds_write2st64_b32 v91, v50, v51 offset0:2 offset1:3
	ds_write2st64_b32 v91, v52, v53 offset0:4 offset1:5
	ds_write2st64_b32 v91, v54, v55 offset0:6 offset1:7
	ds_write2st64_b32 v91, v56, v57 offset0:8 offset1:9
	ds_write2st64_b32 v91, v58, v59 offset0:10 offset1:11
	ds_write2st64_b32 v91, v60, v61 offset0:12 offset1:13
	ds_write2st64_b32 v91, v62, v63 offset0:14 offset1:15
	ds_write2st64_b32 v91, v32, v33 offset0:16 offset1:17
	ds_write2st64_b32 v91, v34, v35 offset0:18 offset1:19
	v_add_u32_e32 v32, 0x1c000, v90
	ds_write2st64_b32 v91, v36, v37 offset0:20 offset1:21
	ds_write2st64_b32 v91, v38, v39 offset0:22 offset1:23
	ds_write2st64_b32 v91, v40, v41 offset0:24 offset1:25
	ds_write2st64_b32 v91, v42, v43 offset0:26 offset1:27
	ds_write2st64_b32 v91, v44, v45 offset0:28 offset1:29
	ds_write2st64_b32 v91, v46, v47 offset0:30 offset1:31
	ds_write2st64_b32 v91, v16, v17 offset0:32 offset1:33
	ds_write2st64_b32 v91, v18, v19 offset0:34 offset1:35
	ds_write2st64_b32 v91, v20, v21 offset0:36 offset1:37
	ds_write2st64_b32 v91, v22, v23 offset0:38 offset1:39
	ds_write2st64_b32 v91, v24, v25 offset0:40 offset1:41
	ds_write2st64_b32 v91, v26, v27 offset0:42 offset1:43
	ds_write2st64_b32 v91, v28, v29 offset0:44 offset1:45
	ds_write2st64_b32 v91, v30, v31 offset0:46 offset1:47
	s_nop 11
	ds_write2st64_b32 v91, v0, v1 offset0:48 offset1:49
	ds_write2st64_b32 v91, v2, v3 offset0:50 offset1:51
	ds_write2st64_b32 v91, v4, v5 offset0:52 offset1:53
	ds_write2st64_b32 v91, v6, v7 offset0:54 offset1:55
	ds_write2st64_b32 v91, v8, v9 offset0:56 offset1:57
	ds_write2st64_b32 v91, v10, v11 offset0:58 offset1:59
	ds_write2st64_b32 v91, v12, v13 offset0:60 offset1:61
	ds_write2st64_b32 v91, v14, v15 offset0:62 offset1:63
	v_ashrrev_i32_e32 v0, 7, v66
	v_lshlrev_b32_e32 v1, 1, v117
	v_and_b32_e32 v22, 2, v1
	v_lshlrev_b32_e32 v23, 12, v0
	v_lshl_or_b32 v26, v22, 10, v23
	v_add_u32_e32 v20, v90, v26
	s_waitcnt lgkmcnt(0)
	s_barrier
; DI bf16_t f2bf(float x) { return (bf16_t)(cvt_pk(x, 0.f) & 0xffffu); }
; DI size_t vf_off(int item, int dvh, int j) { return ((size_t)((item * 16 + (dvh >> 5)) * 4 + (j >> 4)) * 64 + ((j >> 3) & 1) * 32 + (dvh & 31)) * 8 + (j & 7); }
;     ...
;     } else if (EPI == EPI_E5B) {
;         const u32x2 ov = *(const u32x2*)((const bf16_t*)(p.ws + OFF_VT1) + vf_off((((pos + 48) >> 6) * 4 + b) * 4 + (col >> 9), col & 511, (pos + 48) & 63));
;         bf16_t* d = (bf16_t*)(p.ws + OFF_YB) + (size_t)row0 * 2048 + col;
; #pragma unroll
;         for (int e = 0; e < 4; ++e) {
;             const unsigned ob = (e & 1) ? (ov[e >> 1] & 0xffff0000u) : (ov[e >> 1] << 16);
;             const float o = __uint_as_float(ob);
;             const float gte = v[e] / (1.f + __expf(-v[e]));
;             d[(size_t)e * 2048] = f2bf(gte * o * s_aux[lrow0 + e]);
;         }
; template <int EPI, int K, int LNI>
; DI void gemm_tail_unit(const Params& p, const bf16_t* __restrict__ A, const bf16_t* __restrict__ Bt, const int un, float* s_aux) {
;     ...
;     {
;         const int tile = w >> 1, i = tile >> 1, j = tile & 1;
; #pragma unroll
;         for (int gg = 0; gg < 2; ++gg) {
;             const int g = 2 * (w & 1) + gg;
;             float v[4];
; #pragma unroll
;             for (int e = 0; e < 4; ++e) {
;                 float sacc = 0.f;
; #pragma unroll
;                 for (int wv = 0; wv < 8; ++wv) sacc += red[((wv * 4 + tile) * 16 + 4 * g + e) * 64 + lane];
;                 v[e] = sacc;
;             }
;             const int lrow0 = i * 32 + 8 * g + 4 * h;
	ds_read2st64_b32 v[4:5], v20 offset1:1
	ds_read2st64_b32 v[6:7], v20 offset0:64 offset1:65
	v_ashrrev_i32_e32 v1, 3, v66
	v_and_b32_e32 v1, 0xffffffe0, v1
	v_lshl_or_b32 v24, v116, 2, v1
	s_waitcnt lgkmcnt(1)
	v_add_f32_e32 v4, 0, v4
	v_lshl_or_b32 v27, v22, 3, v24
	s_waitcnt lgkmcnt(0)
	v_add_f32_e32 v6, v4, v6
	v_add_u32_e32 v4, 0x8000, v27
	v_mul_hi_i32 v16, v4, s28
	v_lshrrev_b32_e32 v17, 31, v16
	v_ashrrev_i32_e32 v16, 12, v16
	v_add_u32_e32 v16, v16, v17
	v_lshlrev_b32_e32 v0, 5, v0
	v_mul_i32_i24_e32 v17, 0xffffdff0, v16
	v_and_b32_e32 v0, 32, v0
	v_add3_u32 v18, v27, v17, s29
	v_add_u32_e32 v1, s3, v0
	v_lshrrev_b32_e32 v17, 4, v18
	v_lshrrev_b32_e32 v1, 3, v1
	v_and_b32_e32 v19, 0xfffffc, v17
	v_and_or_b32 v25, v1, 60, v69
	v_add_u32_e32 v16, v19, v16
	v_lshl_add_u32 v16, v16, 8, v25
	v_and_or_b32 v16, v17, 3, v16
	v_ashrrev_i32_e32 v17, 31, v16
	v_lshlrev_b32_e32 v18, 2, v18
	v_lshlrev_b64 v[16:17], 6, v[16:17]
	v_and_b32_e32 v18, 32, v18
	v_lshl_add_u64 v[2:3], s[20:21], 0, v[64:65]
	v_or3_b32 v16, v16, v18, v67
	v_lshl_add_u64 v[16:17], v[16:17], 4, v[2:3]
	ds_read2st64_b32 v[8:9], v20 offset0:66 offset1:67
	ds_read2st64_b32 v[10:11], v20 offset0:2 offset1:3
	ds_read2st64_b32 v[12:13], v20 offset0:128 offset1:129
	ds_read2st64_b32 v[14:15], v20 offset0:192 offset1:193
	global_load_dwordx2 v[16:17], v[16:17], off
	v_add_u32_e32 v28, 0x10000, v90
	v_add_u32_e32 v29, 0x14000, v90
	s_waitcnt lgkmcnt(1)
	v_add_f32_e32 v6, v6, v12
	v_add_u32_e32 v30, 0x18000, v90
	v_or_b32_e32 v34, 0x100, v26
	v_add_f32_e32 v5, 0, v5
	s_waitcnt lgkmcnt(0)
	v_add_f32_e32 v6, v6, v14
	v_add_u32_e32 v12, v28, v26
	v_add_u32_e32 v14, v29, v26
	v_add_u32_e32 v31, v30, v26
	v_add_u32_e32 v33, v32, v26
	v_add_u32_e32 v35, v28, v34
	v_add_u32_e32 v36, v29, v34
	v_add_u32_e32 v37, v30, v34
	v_add_u32_e32 v34, v32, v34
	v_add_f32_e32 v5, v5, v7
	ds_read2st64_b32 v[18:19], v20 offset0:194 offset1:195
	ds_read2st64_b32 v[20:21], v20 offset0:130 offset1:131
	ds_read_b32 v12, v12
	ds_read_b32 v14, v14
	ds_read_b32 v31, v31
	ds_read_b32 v33, v33
	ds_read_b32 v35, v35
	ds_read_b32 v36, v36
	ds_read_b32 v37, v37
	ds_read_b32 v34, v34
	s_waitcnt lgkmcnt(7)
	v_add_f32_e32 v6, v6, v12
	v_add_f32_e32 v5, v5, v13
	s_waitcnt lgkmcnt(6)
	v_add_f32_e32 v6, v6, v14
	v_add_f32_e32 v5, v5, v15
	s_waitcnt lgkmcnt(5)
	v_add_f32_e32 v6, v6, v31
	s_waitcnt lgkmcnt(3)
	v_add_f32_e32 v5, v5, v35
	v_add_f32_e32 v12, v6, v33
	s_waitcnt lgkmcnt(2)
	v_add_f32_e32 v5, v5, v36
	v_add_f32_e32 v6, 0, v10
	s_waitcnt lgkmcnt(1)
	v_add_f32_e32 v5, v5, v37
	v_add_f32_e32 v6, v6, v8
	s_waitcnt lgkmcnt(0)
	v_add_f32_e32 v13, v5, v34
	v_or_b32_e32 v5, 0x200, v26
	v_add_f32_e32 v6, v6, v20
	v_or_b32_e32 v14, 0x300, v26
	v_add_f32_e32 v6, v6, v18
	v_add_u32_e32 v7, v28, v5
	v_add_u32_e32 v8, v29, v5
	v_add_u32_e32 v10, v30, v5
	v_add_u32_e32 v5, v32, v5
	v_add_u32_e32 v15, v28, v14
	v_add_u32_e32 v18, v29, v14
	v_add_u32_e32 v20, v30, v14
	v_add_u32_e32 v14, v32, v14
	ds_read_b32 v7, v7
	ds_read_b32 v8, v8
	ds_read_b32 v10, v10
	ds_read_b32 v5, v5
	ds_read_b32 v15, v15
	ds_read_b32 v18, v18
	ds_read_b32 v20, v20
	ds_read_b32 v14, v14
	s_waitcnt lgkmcnt(7)
	v_add_f32_e32 v6, v6, v7
	s_waitcnt lgkmcnt(6)
	v_add_f32_e32 v6, v6, v8
	s_waitcnt lgkmcnt(5)
	v_add_f32_e32 v6, v6, v10
	s_waitcnt lgkmcnt(4)
	v_add_f32_e32 v10, v6, v5
	v_add_f32_e32 v5, 0, v11
	v_add_f32_e32 v5, v5, v9
	v_add_f32_e32 v5, v5, v21
	v_mul_f32_e32 v6, 0xbfb8aa3b, v12
	v_add_f32_e32 v5, v5, v19
	v_exp_f32_e32 v6, v6
	s_waitcnt lgkmcnt(3)
	v_add_f32_e32 v5, v5, v15
	s_waitcnt lgkmcnt(2)
	v_add_f32_e32 v5, v5, v18
	s_waitcnt lgkmcnt(1)
	v_add_f32_e32 v5, v5, v20
	s_waitcnt lgkmcnt(0)
	v_add_f32_e32 v11, v5, v14
	v_add_f32_e32 v14, 1.0, v6
	v_add_u32_e32 v0, v106, v0
	v_ashrrev_i32_e32 v1, 31, v0
	v_ashrrev_i32_e32 v5, 31, v4
	v_lshl_add_u64 v[0:1], v[0:1], 1, s[36:37]
	v_lshlrev_b64 v[4:5], 12, v[4:5]
	v_lshl_add_u64 v[8:9], v[0:1], 0, v[4:5]
	v_lshl_add_u32 v4, v27, 2, s35
	ds_read_b128 v[4:7], v4
	v_mul_f32_e32 v19, 0xbfb8aa3b, v13
	v_exp_f32_e32 v19, v19
	s_waitcnt vmcnt(0)
	v_lshlrev_b32_e32 v15, 16, v16
	v_rcp_f32_e32 v18, v14
	s_nop 0
	v_mul_f32_e32 v12, v12, v18
	v_mul_f32_e32 v12, v12, v15
	s_waitcnt lgkmcnt(0)
	v_mul_f32_e32 v4, v4, v12
	v_add_f32_e32 v12, 1.0, v19
	v_cvt_pk_bf16_f32 v4, v4, s0
	global_store_short v[8:9], v4, off
	v_and_b32_e32 v4, 0xffff0000, v16
	v_rcp_f32_e32 v14, v12
	s_nop 0
	v_mul_f32_e32 v12, v13, v14
	v_mul_f32_e32 v13, 0xbfb8aa3b, v10
	v_exp_f32_e32 v13, v13
	v_mul_f32_e32 v4, v12, v4
	v_mul_f32_e32 v4, v5, v4
	v_cvt_pk_bf16_f32 v12, v4, s0
	v_add_f32_e32 v13, 1.0, v13
	v_add_co_u32_e32 v4, vcc, s42, v8
	s_add_i32 s3, s3, s14
	s_nop 0
	v_addc_co_u32_e32 v5, vcc, 0, v9, vcc
	v_mul_f32_e32 v15, 0xbfb8aa3b, v11
	v_exp_f32_e32 v15, v15
	global_store_short v[4:5], v12, off offset:-4096
	v_lshlrev_b32_e32 v12, 16, v17
	v_rcp_f32_e32 v14, v13
	s_nop 0
	v_mul_f32_e32 v10, v10, v14
	v_mul_f32_e32 v10, v10, v12
	v_mul_f32_e32 v6, v10, v6
	v_add_f32_e32 v10, 1.0, v15
	v_cvt_pk_bf16_f32 v6, v6, s0
	global_store_short v[4:5], v6, off
	v_and_b32_e32 v4, 0xffff0000, v17
	v_or_b32_e32 v12, 1, v22
	v_rcp_f32_e32 v5, v10
	s_nop 0
	v_mul_f32_e32 v5, v11, v5
	v_lshl_or_b32 v20, v12, 10, v23
	v_mul_f32_e32 v4, v5, v4
	v_add_u32_e32 v18, v90, v20
	v_mul_f32_e32 v4, v4, v7
	ds_read2st64_b32 v[6:7], v18 offset1:1
	v_lshl_or_b32 v21, v12, 3, v24
	v_cvt_pk_bf16_f32 v10, v4, s0
	v_add_co_u32_e32 v4, vcc, s43, v8
	s_waitcnt lgkmcnt(0)
; DI float ex2(float x) { return __builtin_amdgcn_exp2f(x); }
; template <int EPI, int K, int LNI>
; DI void gemm_tail_unit(const Params& p, const bf16_t* __restrict__ A, const bf16_t* __restrict__ Bt, const int un, float* s_aux) {
;     ...
;     {
;         const int tile = w >> 1, i = tile >> 1, j = tile & 1;
; #pragma unroll
;         for (int gg = 0; gg < 2; ++gg) {
;             const int g = 2 * (w & 1) + gg;
;             float v[4];
; #pragma unroll
;             for (int e = 0; e < 4; ++e) {
;                 float sacc = 0.f;
; #pragma unroll
;                 for (int wv = 0; wv < 8; ++wv) sacc += red[((wv * 4 + tile) * 16 + 4 * g + e) * 64 + lane];
;                 v[e] = sacc;
;             }
;             const int lrow0 = i * 32 + 8 * g + 4 * h;
;             f32x2 rs[4]; float lng = 1.f, lnb = 0.f;
;             if (EPI == EPI_E5) {
;                 lng = log2f(1.f - ex2(-5.f - (float)((col0 >> 8) & 3)));
;                 const int idx_ = (((ROW0 + lrow0) % LT) + 48) & 63;
; #pragma unroll
;                 for (int e = 0; e < 4; ++e) rs[e] = (f32x2){ex2(lng * (float)(idx_ + e + 1)), 0.0625f * ex2(lng * (float)(63 - idx_ - e))};
;             }
;             if (EPI == EPI_RESID && LNI >= 0) {
;                 const f32x2* st_ = (const f32x2*)((unsigned char*)p.out + OFFO_STATS) + ROW0 + lrow0;
; #pragma unroll
;                 for (int e = 0; e < 4; ++e) rs[e] = st_[e];
;                 lng = p.ln_g[(LNI < 0 ? 0 : LNI) * 1024 + col0 + j * 32 + r]; lnb = p.ln_b[(LNI < 0 ? 0 : LNI) * 1024 + col0 + j * 32 + r];
;             }
;             epi_store<EPI, LNI>(p, ROW0 + lrow0, col0 + j * 32 + r, lrow0, v, s_aux, rs, lng, lnb);
;         }
;     }
;     __syncthreads();
	v_add_f32_e32 v16, 0, v6
	v_add_u32_e32 v6, 0x8000, v21
	v_mul_hi_i32 v12, v6, s28
	v_lshrrev_b32_e32 v13, 31, v12
	v_ashrrev_i32_e32 v12, 12, v12
	v_add_u32_e32 v12, v12, v13
	v_mul_i32_i24_e32 v13, 0xffffdff0, v12
	v_add3_u32 v14, v21, v13, s29
	v_lshrrev_b32_e32 v13, 4, v14
	v_and_b32_e32 v15, 0xfffffc, v13
	v_add_u32_e32 v12, v15, v12
	v_lshl_add_u32 v12, v12, 8, v25
	v_and_or_b32 v12, v13, 3, v12
	v_ashrrev_i32_e32 v13, 31, v12
	v_lshlrev_b32_e32 v14, 2, v14
	v_lshlrev_b64 v[12:13], 6, v[12:13]
	v_and_b32_e32 v14, 32, v14
	v_addc_co_u32_e32 v5, vcc, 0, v9, vcc
	v_or3_b32 v12, v12, v14, v67
	global_store_short v[4:5], v10, off
	v_lshl_add_u64 v[2:3], v[12:13], 4, v[2:3]
	ds_read2st64_b32 v[4:5], v18 offset0:64 offset1:65
	ds_read2st64_b32 v[8:9], v18 offset0:66 offset1:67
	ds_read2st64_b32 v[10:11], v18 offset0:2 offset1:3
	global_load_dwordx2 v[12:13], v[2:3], off
	ds_read2st64_b32 v[2:3], v18 offset0:128 offset1:129
	ds_read2st64_b32 v[14:15], v18 offset0:192 offset1:193
	s_waitcnt lgkmcnt(4)
	v_add_f32_e32 v4, v16, v4
	v_or_b32_e32 v24, 0x100, v20
	v_add_u32_e32 v22, v30, v20
	s_waitcnt lgkmcnt(1)
	v_add_f32_e32 v2, v4, v2
	s_waitcnt lgkmcnt(0)
	v_add_f32_e32 v2, v2, v14
	v_add_u32_e32 v4, v28, v20
	v_add_u32_e32 v14, v29, v20
	v_add_u32_e32 v23, v32, v20
	v_add_u32_e32 v25, v28, v24
	v_add_u32_e32 v26, v29, v24
	v_add_u32_e32 v27, v30, v24
	v_add_u32_e32 v24, v32, v24
	ds_read2st64_b32 v[16:17], v18 offset0:194 offset1:195
	ds_read2st64_b32 v[18:19], v18 offset0:130 offset1:131
	ds_read_b32 v4, v4
	ds_read_b32 v14, v14
	ds_read_b32 v22, v22
	ds_read_b32 v23, v23
	ds_read_b32 v25, v25
	ds_read_b32 v26, v26
	ds_read_b32 v27, v27
	ds_read_b32 v24, v24
	s_waitcnt lgkmcnt(7)
	v_add_f32_e32 v2, v2, v4
	s_waitcnt lgkmcnt(6)
	v_add_f32_e32 v2, v2, v14
	s_waitcnt lgkmcnt(5)
	v_add_f32_e32 v2, v2, v22
	s_waitcnt lgkmcnt(4)
	v_add_f32_e32 v14, v2, v23
	v_add_f32_e32 v2, 0, v7
	v_add_f32_e32 v2, v2, v5
	v_add_f32_e32 v2, v2, v3
	v_add_f32_e32 v2, v2, v15
	s_waitcnt lgkmcnt(3)
	v_add_f32_e32 v2, v2, v25
	s_waitcnt lgkmcnt(2)
	v_add_f32_e32 v2, v2, v26
	v_add_f32_e32 v3, 0, v10
	s_waitcnt lgkmcnt(1)
	v_add_f32_e32 v2, v2, v27
	v_add_f32_e32 v3, v3, v8
	s_waitcnt lgkmcnt(0)
	v_add_f32_e32 v15, v2, v24
	v_or_b32_e32 v2, 0x200, v20
	v_add_f32_e32 v3, v3, v18
	v_or_b32_e32 v8, 0x300, v20
	v_add_f32_e32 v3, v3, v16
	v_add_u32_e32 v4, v28, v2
	v_add_u32_e32 v5, v29, v2
	v_add_u32_e32 v7, v30, v2
	v_add_u32_e32 v2, v32, v2
	v_add_u32_e32 v10, v28, v8
	v_add_u32_e32 v16, v29, v8
	v_add_u32_e32 v18, v30, v8
	v_add_u32_e32 v8, v32, v8
	ds_read_b32 v4, v4
	ds_read_b32 v5, v5
	ds_read_b32 v7, v7
	ds_read_b32 v2, v2
	ds_read_b32 v10, v10
	ds_read_b32 v16, v16
	ds_read_b32 v18, v18
	ds_read_b32 v8, v8
	s_waitcnt lgkmcnt(7)
	v_add_f32_e32 v3, v3, v4
	s_waitcnt lgkmcnt(6)
	v_add_f32_e32 v3, v3, v5
	s_waitcnt lgkmcnt(5)
	v_add_f32_e32 v3, v3, v7
	s_waitcnt lgkmcnt(4)
	v_add_f32_e32 v20, v3, v2
	v_mul_f32_e32 v3, 0xbfb8aa3b, v14
	v_exp_f32_e32 v3, v3
	v_add_f32_e32 v2, 0, v11
	v_add_f32_e32 v2, v2, v9
	v_add_f32_e32 v2, v2, v19
	v_add_f32_e32 v2, v2, v17
	v_add_f32_e32 v9, 1.0, v3
	s_waitcnt lgkmcnt(3)
	v_add_f32_e32 v2, v2, v10
	s_waitcnt lgkmcnt(2)
	v_add_f32_e32 v2, v2, v16
	s_waitcnt lgkmcnt(1)
	v_add_f32_e32 v2, v2, v18
	v_ashrrev_i32_e32 v7, 31, v6
	s_waitcnt lgkmcnt(0)
	v_add_f32_e32 v8, v2, v8
	v_lshlrev_b64 v[2:3], 12, v[6:7]
	v_lshl_add_u64 v[4:5], v[0:1], 0, v[2:3]
	v_lshl_add_u32 v0, v21, 2, s35
	ds_read_b128 v[0:3], v0
	v_mul_f32_e32 v10, 0xbfb8aa3b, v15
	v_exp_f32_e32 v10, v10
	v_rcp_f32_e32 v7, v9
	s_nop 0
	v_mul_f32_e32 v7, v14, v7
	s_cmp_lt_i32 s45, 32
	s_waitcnt vmcnt(0)
	v_lshlrev_b32_e32 v6, 16, v12
	v_mul_f32_e32 v6, v7, v6
	s_waitcnt lgkmcnt(0)
	v_mul_f32_e32 v0, v0, v6
	v_add_f32_e32 v6, 1.0, v10
	v_cvt_pk_bf16_f32 v0, v0, s0
	global_store_short v[4:5], v0, off
	v_and_b32_e32 v0, 0xffff0000, v12
	v_rcp_f32_e32 v7, v6
	s_nop 0
	v_mul_f32_e32 v6, v15, v7
	v_mul_f32_e32 v7, 0xbfb8aa3b, v20
	v_exp_f32_e32 v7, v7
	v_mul_f32_e32 v0, v6, v0
	v_mul_f32_e32 v0, v1, v0
	v_cvt_pk_bf16_f32 v6, v0, s0
	v_add_f32_e32 v7, 1.0, v7
	v_add_co_u32_e32 v0, vcc, s42, v4
	s_nop 0
	s_nop 0
	v_addc_co_u32_e32 v1, vcc, 0, v5, vcc
	v_mul_f32_e32 v10, 0xbfb8aa3b, v8
	v_exp_f32_e32 v10, v10
	global_store_short v[0:1], v6, off offset:-4096
	v_lshlrev_b32_e32 v6, 16, v13
	v_rcp_f32_e32 v9, v7
	s_nop 0
	v_mul_f32_e32 v7, v20, v9
	v_mul_f32_e32 v6, v7, v6
	v_mul_f32_e32 v2, v6, v2
	v_add_f32_e32 v6, 1.0, v10
	v_cvt_pk_bf16_f32 v2, v2, s0
	global_store_short v[0:1], v2, off
	v_and_b32_e32 v0, 0xffff0000, v13
	v_rcp_f32_e32 v1, v6
	s_nop 0
	v_mul_f32_e32 v1, v8, v1
	v_mul_f32_e32 v0, v1, v0
	v_mul_f32_e32 v0, v0, v3
	v_cvt_pk_bf16_f32 v2, v0, s0
	v_add_co_u32_e32 v0, vcc, 0x3000, v4
	s_nop 1
	v_addc_co_u32_e32 v1, vcc, 0, v5, vcc
	global_store_short v[0:1], v2, off
	s_barrier
	s_cbranch_scc0 .LBB0_1649
